# diff-attn fast loop: K/V DMA scalar addresses and m0 computed before the per-tile barrier so the 4 LDS-DMA loads issue immediately after it
# baseline (speedup 1.0000x reference)
.Lfast_loop:
	s_add_u32 s80, s74, s42
	s_addc_u32 s81, s75, s43
	s_add_i32 s4, s55, 0x8000
	s_add_u32 s82, s76, s42
	s_addc_u32 s83, s77, s43
	s_add_u32 s84, s82, 0x54000
	s_addc_u32 s85, s83, 0
	s_mov_b32 m0, s4
	s_waitcnt vmcnt(0)
	s_barrier
	global_load_lds_dwordx4 v254, s[80:81]
	s_add_i32 m0, s4, 0x1f80
	s_nop 0
	global_load_lds_dwordx4 v254, s[80:81] offset:128
	s_add_i32 m0, s4, 0x4000
	s_nop 0
	global_load_lds_dwordx4 v255, s[82:83]
	s_add_i32 m0, s4, 0x6000
	s_nop 0
	global_load_lds_dwordx4 v255, s[84:85]
	ds_read_b128 v[6:9], v236
	ds_read_b128 v[178:181], v226
	ds_read_b128 v[182:185], v226 offset:4096
	ds_read_b128 v[10:13], v236 offset:32
	ds_read_b128 v[186:189], v227
	ds_read_b128 v[190:193], v227 offset:4096
	ds_read_b128 v[14:17], v236 offset:64
	ds_read_b128 v[194:197], v228
	ds_read_b128 v[198:201], v228 offset:4096
	ds_read_b128 v[238:241], v236 offset:96
	ds_read_b128 v[202:205], v230
	ds_read_b128 v[206:209], v230 offset:4096
	s_waitcnt lgkmcnt(9)
	v_mfma_f32_32x32x16_bf16 v[162:177], v[178:181], v[6:9], 0
	v_mfma_f32_32x32x16_bf16 v[146:161], v[182:185], v[6:9], 0
	ds_read_b128 v[246:249], v236 offset:128
	ds_read_b128 v[250:253], v226 offset:8192
	ds_read_b128 v[6:9], v226 offset:12288
	s_waitcnt lgkmcnt(9)
	v_mfma_f32_32x32x16_bf16 v[162:177], v[186:189], v[10:13], v[162:177]
	v_mfma_f32_32x32x16_bf16 v[146:161], v[190:193], v[10:13], v[146:161]
	ds_read_b128 v[10:13], v236 offset:160
	s_waitcnt lgkmcnt(7)
	v_mfma_f32_32x32x16_bf16 v[162:177], v[194:197], v[14:17], v[162:177]
	v_mfma_f32_32x32x16_bf16 v[146:161], v[198:201], v[14:17], v[146:161]
	ds_read_b128 v[14:17], v227 offset:8192
	s_waitcnt lgkmcnt(5)
	v_mfma_f32_32x32x16_bf16 v[162:177], v[202:205], v[238:241], v[162:177]
	v_mfma_f32_32x32x16_bf16 v[146:161], v[206:209], v[238:241], v[146:161]
	ds_read_b128 v[238:241], v227 offset:12288
	s_waitcnt lgkmcnt(3)
	v_mfma_f32_32x32x16_bf16 v[194:209], v[250:253], v[246:249], 0
	v_mfma_f32_32x32x16_bf16 v[178:193], v[6:9], v[246:249], 0
	ds_read_b128 v[246:249], v236 offset:192
	ds_read_b128 v[250:253], v228 offset:8192
	ds_read_b128 v[6:9], v228 offset:12288
	s_waitcnt lgkmcnt(3)
	v_mfma_f32_32x32x16_bf16 v[194:209], v[14:17], v[10:13], v[194:209]
	v_mfma_f32_32x32x16_bf16 v[178:193], v[238:241], v[10:13], v[178:193]
	ds_read_b128 v[10:13], v236 offset:224
	ds_read_b128 v[14:17], v230 offset:8192
	ds_read_b128 v[238:241], v230 offset:12288
	s_waitcnt lgkmcnt(3)
	v_mfma_f32_32x32x16_bf16 v[194:209], v[250:253], v[246:249], v[194:209]
	v_mfma_f32_32x32x16_bf16 v[178:193], v[6:9], v[246:249], v[178:193]
	s_waitcnt lgkmcnt(0)
	v_mfma_f32_32x32x16_bf16 v[194:209], v[14:17], v[10:13], v[194:209]
	v_mfma_f32_32x32x16_bf16 v[178:193], v[238:241], v[10:13], v[178:193]
	v_exp_f32_e32 v166, v166
	v_exp_f32_e32 v167, v167
	v_exp_f32_e32 v168, v168
	v_exp_f32_e32 v169, v169
	s_nop 6
	v_exp_f32_e32 v2, v194
	v_exp_f32_e32 v194, v195
	v_exp_f32_e32 v195, v196
	v_exp_f32_e32 v196, v197
	v_exp_f32_e32 v197, v198
	v_exp_f32_e32 v198, v199
	v_exp_f32_e32 v199, v200
	v_exp_f32_e32 v200, v201
	v_exp_f32_e32 v201, v162
	v_exp_f32_e32 v237, v163
	v_exp_f32_e32 v238, v164
	v_exp_f32_e32 v239, v165
	v_cvt_pk_bf16_f32 v6, v201, v237
	v_cvt_pk_bf16_f32 v7, v238, v239
	v_cvt_pk_bf16_f32 v8, v166, v167
	v_cvt_pk_bf16_f32 v9, v168, v169
	ds_read_b64_tr_b16 v[10:11], v231 offset:16384
	ds_read_b64_tr_b16 v[12:13], v231 offset:18432
	v_cvt_pk_bf16_f32 v14, v2, v194
	ds_read_b64_tr_b16 v[162:163], v232 offset:16384
	ds_read_b64_tr_b16 v[164:165], v232 offset:18432
	v_cvt_pk_bf16_f32 v15, v195, v196
	v_cvt_pk_bf16_f32 v16, v197, v198
	v_cvt_pk_bf16_f32 v17, v199, v200
	s_waitcnt lgkmcnt(2)
	v_mfma_f32_32x32x16_bf16 v[82:97], v[6:9], v[10:13], v[82:97]
	v_exp_f32_e32 v202, v202
	v_exp_f32_e32 v203, v203
	v_exp_f32_e32 v204, v204
	v_exp_f32_e32 v205, v205
	v_exp_f32_e32 v206, v206
	v_exp_f32_e32 v207, v207
	v_exp_f32_e32 v208, v208
	v_mfma_f32_32x32x16_bf16 v[130:145], v[14:17], v[10:13], v[130:145]
	ds_read_b64_tr_b16 v[10:11], v233 offset:16384
	ds_read_b64_tr_b16 v[12:13], v233 offset:18432
	v_exp_f32_e32 v170, v170
	v_exp_f32_e32 v171, v171
	v_exp_f32_e32 v172, v172
	v_exp_f32_e32 v173, v173
	v_exp_f32_e32 v174, v174
	v_exp_f32_e32 v175, v175
	s_waitcnt lgkmcnt(2)
	v_mfma_f32_32x32x16_bf16 v[66:81], v[6:9], v[162:165], v[66:81]
	v_exp_f32_e32 v176, v176
	v_exp_f32_e32 v177, v177
	v_exp_f32_e32 v209, v209
	v_exp_f32_e32 v178, v178
	v_exp_f32_e32 v179, v179
	v_exp_f32_e32 v180, v180
	v_exp_f32_e32 v181, v181
	v_mfma_f32_32x32x16_bf16 v[114:129], v[14:17], v[162:165], v[114:129]
	ds_read_b64_tr_b16 v[162:163], v234 offset:16384
	ds_read_b64_tr_b16 v[164:165], v234 offset:18432
	v_add_f32_e32 v2, v178, v2
	v_add_f32_e32 v2, 0, v2
	v_add_f32_e32 v194, v179, v194
	v_add_f32_e32 v2, v194, v2
	v_add_f32_e32 v194, v180, v195
	s_waitcnt lgkmcnt(2)
	v_mfma_f32_32x32x16_bf16 v[34:49], v[6:9], v[10:13], v[34:49]
	v_add_f32_e32 v2, v194, v2
	v_add_f32_e32 v194, v181, v196
	v_add_f32_e32 v2, v194, v2
	v_exp_f32_e32 v182, v182
	v_exp_f32_e32 v183, v183
	v_exp_f32_e32 v184, v184
	v_exp_f32_e32 v194, v146
	v_mfma_f32_32x32x16_bf16 v[98:113], v[14:17], v[10:13], v[98:113]
	ds_read_b64_tr_b16 v[10:11], v231 offset:20480
	ds_read_b64_tr_b16 v[12:13], v231 offset:22528
	v_exp_f32_e32 v195, v147
	v_exp_f32_e32 v196, v148
	v_exp_f32_e32 v244, v149
	v_exp_f32_e32 v150, v150
	v_exp_f32_e32 v151, v151
	v_exp_f32_e32 v152, v152
	s_waitcnt lgkmcnt(2)
	v_mfma_f32_32x32x16_bf16 v[18:33], v[6:9], v[162:165], v[18:33]
	v_cvt_pk_bf16_f32 v6, v170, v171
	v_cvt_pk_bf16_f32 v7, v172, v173
	v_cvt_pk_bf16_f32 v8, v174, v175
	v_cvt_pk_bf16_f32 v9, v176, v177
	v_exp_f32_e32 v153, v153
	v_exp_f32_e32 v154, v154
	v_exp_f32_e32 v155, v155
	v_mfma_f32_32x32x16_bf16 v[50:65], v[14:17], v[162:165], v[50:65]
	v_cvt_pk_bf16_f32 v14, v202, v203
	ds_read_b64_tr_b16 v[162:163], v232 offset:20480
	ds_read_b64_tr_b16 v[164:165], v232 offset:22528
	v_cvt_pk_bf16_f32 v15, v204, v205
	v_cvt_pk_bf16_f32 v16, v206, v207
	v_cvt_pk_bf16_f32 v17, v208, v209
	v_exp_f32_e32 v156, v156
	s_waitcnt lgkmcnt(2)
	v_mfma_f32_32x32x16_bf16 v[82:97], v[6:9], v[10:13], v[82:97]
	v_exp_f32_e32 v157, v157
	v_exp_f32_e32 v158, v158
	v_exp_f32_e32 v159, v159
	v_exp_f32_e32 v160, v160
	v_exp_f32_e32 v161, v161
	s_add_u32 s42, s42, 0xa8000
	s_addc_u32 s43, s43, 0
	v_mfma_f32_32x32x16_bf16 v[130:145], v[14:17], v[10:13], v[130:145]
	ds_read_b64_tr_b16 v[10:11], v233 offset:20480
	ds_read_b64_tr_b16 v[12:13], v233 offset:22528
	s_waitcnt lgkmcnt(2)
	v_mfma_f32_32x32x16_bf16 v[66:81], v[6:9], v[162:165], v[66:81]
	v_mfma_f32_32x32x16_bf16 v[114:129], v[14:17], v[162:165], v[114:129]
	ds_read_b64_tr_b16 v[162:163], v234 offset:20480
	ds_read_b64_tr_b16 v[164:165], v234 offset:22528
	s_waitcnt lgkmcnt(0)
	v_mfma_f32_32x32x16_bf16 v[18:33], v[6:9], v[162:165], v[18:33]
	v_mfma_f32_32x32x16_bf16 v[50:65], v[14:17], v[162:165], v[50:65]
	v_exp_f32_e32 v162, v185
	v_add_f32_e32 v163, v182, v197
	v_add_f32_e32 v2, v163, v2
	v_add_f32_e32 v163, v183, v198
	v_add_f32_e32 v2, v163, v2
	v_exp_f32_e32 v163, v186
	v_exp_f32_e32 v164, v188
	v_mfma_f32_32x32x16_bf16 v[34:49], v[6:9], v[10:13], v[34:49]
	v_cvt_pk_bf16_f32 v6, v194, v195
	v_cvt_pk_bf16_f32 v7, v196, v244
	v_cvt_pk_bf16_f32 v8, v150, v151
	v_cvt_pk_bf16_f32 v9, v152, v153
	v_exp_f32_e32 v165, v189
	v_mfma_f32_32x32x16_bf16 v[98:113], v[14:17], v[10:13], v[98:113]
	ds_read_b64_tr_b16 v[10:11], v231 offset:24576
	ds_read_b64_tr_b16 v[12:13], v231 offset:26624
	v_cvt_pk_bf16_f32 v14, v178, v179
	v_cvt_pk_bf16_f32 v15, v180, v181
	v_cvt_pk_bf16_f32 v16, v182, v183
	v_cvt_pk_bf16_f32 v17, v184, v162
	ds_read_b64_tr_b16 v[146:147], v232 offset:24576
	ds_read_b64_tr_b16 v[148:149], v232 offset:26624
	v_add_f32_e32 v178, v165, v205
	s_waitcnt lgkmcnt(2)
	v_mfma_f32_32x32x16_bf16 v[82:97], v[6:9], v[10:13], v[82:97]
	v_exp_f32_e32 v179, v190
	s_nop 0
	v_add_f32_e32 v180, v179, v206
	v_mfma_f32_32x32x16_bf16 v[130:145], v[14:17], v[10:13], v[130:145]
	v_add_f32_e32 v10, v184, v199
	v_add_f32_e32 v2, v10, v2
	v_add_f32_e32 v10, v162, v200
	v_exp_f32_e32 v162, v187
	v_add_f32_e32 v2, v10, v2
	v_add_f32_e32 v10, v163, v202
	v_add_f32_e32 v2, v10, v2
	v_add_f32_e32 v10, v162, v203
	v_add_f32_e32 v2, v10, v2
	v_add_f32_e32 v10, v164, v204
	v_add_f32_e32 v2, v10, v2
	v_add_f32_e32 v2, v178, v2
	v_exp_f32_e32 v178, v191
	ds_read_b64_tr_b16 v[10:11], v233 offset:24576
	ds_read_b64_tr_b16 v[12:13], v233 offset:26624
	s_waitcnt lgkmcnt(2)
	v_mfma_f32_32x32x16_bf16 v[66:81], v[6:9], v[146:149], v[66:81]
	v_add_f32_e32 v2, v180, v2
	v_exp_f32_e32 v180, v192
	v_add_f32_e32 v181, v178, v207
	v_add_f32_e32 v2, v181, v2
	v_exp_f32_e32 v181, v193
	v_mfma_f32_32x32x16_bf16 v[114:129], v[14:17], v[146:149], v[114:129]
	ds_read_b64_tr_b16 v[146:147], v234 offset:24576
	ds_read_b64_tr_b16 v[148:149], v234 offset:26624
	s_waitcnt lgkmcnt(2)
	v_mfma_f32_32x32x16_bf16 v[34:49], v[6:9], v[10:13], v[34:49]
	v_mfma_f32_32x32x16_bf16 v[98:113], v[14:17], v[10:13], v[98:113]
	v_add_f32_e32 v10, v180, v208
	v_add_f32_e32 v2, v10, v2
	ds_read_b64_tr_b16 v[10:11], v231 offset:28672
	ds_read_b64_tr_b16 v[12:13], v231 offset:30720
	s_waitcnt lgkmcnt(2)
	v_mfma_f32_32x32x16_bf16 v[18:33], v[6:9], v[146:149], v[18:33]
	v_cvt_pk_bf16_f32 v6, v154, v155
	v_cvt_pk_bf16_f32 v7, v156, v157
	v_cvt_pk_bf16_f32 v8, v158, v159
	v_cvt_pk_bf16_f32 v9, v160, v161
	v_mfma_f32_32x32x16_bf16 v[50:65], v[14:17], v[146:149], v[50:65]
	v_cvt_pk_bf16_f32 v14, v163, v162
	v_cvt_pk_bf16_f32 v15, v164, v165
	v_cvt_pk_bf16_f32 v16, v179, v178
	v_cvt_pk_bf16_f32 v17, v180, v181
	v_add_f32_e32 v162, v181, v209
	v_add_f32_e32 v2, v162, v2
	v_add_f32_e32 v4, v4, v2
	v_add_f32_e32 v2, v194, v201
	s_waitcnt lgkmcnt(0)
	v_mfma_f32_32x32x16_bf16 v[82:97], v[6:9], v[10:13], v[82:97]
	v_add_f32_e32 v2, 0, v2
	ds_read_b64_tr_b16 v[146:147], v232 offset:28672
	ds_read_b64_tr_b16 v[148:149], v232 offset:30720
	v_mfma_f32_32x32x16_bf16 v[130:145], v[14:17], v[10:13], v[130:145]
	v_add_f32_e32 v10, v195, v237
	v_add_f32_e32 v2, v10, v2
	v_add_f32_e32 v10, v196, v238
	v_add_f32_e32 v2, v10, v2
	v_add_f32_e32 v10, v244, v239
	v_add_f32_e32 v2, v10, v2
	v_add_f32_e32 v10, v150, v166
	v_add_f32_e32 v2, v10, v2
	v_add_f32_e32 v10, v151, v167
	v_add_f32_e32 v2, v10, v2
	v_add_f32_e32 v10, v152, v168
	s_waitcnt lgkmcnt(0)
	v_mfma_f32_32x32x16_bf16 v[66:81], v[6:9], v[146:149], v[66:81]
	v_add_f32_e32 v2, v10, v2
	ds_read_b64_tr_b16 v[10:11], v233 offset:28672
	ds_read_b64_tr_b16 v[12:13], v233 offset:30720
	v_add_f32_e32 v150, v153, v169
	v_add_f32_e32 v2, v150, v2
	v_add_f32_e32 v150, v154, v170
	v_add_f32_e32 v2, v150, v2
	v_add_f32_e32 v150, v155, v171
	v_mfma_f32_32x32x16_bf16 v[114:129], v[14:17], v[146:149], v[114:129]
	ds_read_b64_tr_b16 v[146:147], v234 offset:28672
	ds_read_b64_tr_b16 v[148:149], v234 offset:30720
	v_add_f32_e32 v2, v150, v2
	v_add_f32_e32 v150, v156, v172
	v_add_f32_e32 v2, v150, v2
	v_add_f32_e32 v150, v157, v173
	v_add_f32_e32 v2, v150, v2
	s_waitcnt lgkmcnt(2)
	v_mfma_f32_32x32x16_bf16 v[34:49], v[6:9], v[10:13], v[34:49]
	v_mfma_f32_32x32x16_bf16 v[98:113], v[14:17], v[10:13], v[98:113]
	v_add_f32_e32 v10, v158, v174
	v_add_f32_e32 v2, v10, v2
	v_add_f32_e32 v10, v159, v175
	v_add_f32_e32 v2, v10, v2
	v_add_f32_e32 v10, v160, v176
	v_add_f32_e32 v2, v10, v2
	v_add_f32_e32 v10, v161, v177
	s_waitcnt lgkmcnt(0)
	v_mfma_f32_32x32x16_bf16 v[18:33], v[6:9], v[146:149], v[18:33]
	v_add_f32_e32 v2, v10, v2
	v_add_f32_e32 v235, v235, v2
	v_mfma_f32_32x32x16_bf16 v[50:65], v[14:17], v[146:149], v[50:65]
	s_add_u32 s80, s74, s42
	s_addc_u32 s81, s75, s43
	s_add_i32 s4, s55, 0
	s_add_u32 s82, s76, s42
	s_addc_u32 s83, s77, s43
	s_add_u32 s84, s82, 0x54000
	s_addc_u32 s85, s83, 0
	s_mov_b32 m0, s4
	s_cmp_eq_u32 s42, 0x5358000
	s_waitcnt vmcnt(0)
	s_barrier
	s_cbranch_scc1 .Lfast_skip_dma
	global_load_lds_dwordx4 v254, s[80:81]
	s_add_i32 m0, s4, 0x1f80
	s_nop 0
	global_load_lds_dwordx4 v254, s[80:81] offset:128
	s_add_i32 m0, s4, 0x4000
	s_nop 0
	global_load_lds_dwordx4 v255, s[82:83]
	s_add_i32 m0, s4, 0x6000
	s_nop 0
	global_load_lds_dwordx4 v255, s[84:85]
